# speedup vs baseline: 1.0411x; 1.0069x over previous
.LBB0_33:
	s_or_b64 exec, exec, s[6:7]
	v_mov_b32_e32 v0, 0xbb64000
	buffer_wbl2 sc1
	s_waitcnt vmcnt(0)
	buffer_inv sc1
	global_load_dword v2, v0, s[84:85] offset:1280 sc1
	global_load_dword v4, v0, s[84:85] offset:1536 sc1
	global_load_dword v5, v0, s[84:85] offset:1792 sc1
	global_load_dword v6, v0, s[84:85] offset:2048 sc1
	global_load_dword v7, v0, s[84:85] offset:2304 sc1
	global_load_dword v8, v0, s[84:85] offset:2560 sc1
	global_load_dword v9, v0, s[84:85] offset:2816 sc1
	global_load_dword v10, v0, s[84:85] offset:3072 sc1
	global_load_dword v11, v0, s[84:85] offset:3328 sc1
	global_load_dword v12, v0, s[84:85] offset:3584 sc1
	global_load_dword v13, v0, s[84:85] offset:3840 sc1
	v_mov_b32_e32 v0, 0xbb65000
	global_load_dword v14, v0, s[84:85] sc1
	global_load_dword v15, v0, s[84:85] offset:256 sc1
	global_load_dword v16, v0, s[84:85] offset:512 sc1
	global_load_dword v17, v0, s[84:85] offset:768 sc1
	global_load_dword v18, v0, s[84:85] offset:1024 sc1
	v_mov_b32_e32 v3, 0
	global_load_dword v1, v3, s[4:5] offset:1024 sc1
	s_add_i32 s4, 0, 0x200f0
	v_mov_b32_e32 v0, s24
	s_waitcnt vmcnt(16)
	v_cmp_ne_u32_e32 vcc, 0, v2
	s_nop 1
	v_cndmask_b32_e64 v2, 0, 1, vcc
	s_waitcnt vmcnt(14)
	v_cmp_ne_u32_e32 vcc, 0, v5
	s_nop 1
	v_cndmask_b32_e64 v5, 0, 1, vcc
	s_waitcnt vmcnt(12)
	v_cmp_ne_u32_e32 vcc, 0, v7
	s_nop 1
	v_cndmask_b32_e64 v7, 0, 1, vcc
	s_waitcnt vmcnt(10)
	v_cmp_ne_u32_e32 vcc, 0, v9
	s_nop 1
	v_cndmask_b32_e64 v9, 0, 1, vcc
	s_waitcnt vmcnt(8)
	v_cmp_ne_u32_e32 vcc, 0, v11
	s_nop 1
	v_cndmask_b32_e64 v11, 0, 1, vcc
	s_waitcnt vmcnt(6)
	v_cmp_ne_u32_e32 vcc, 0, v13
	s_nop 1
	v_cndmask_b32_e64 v13, 0, 1, vcc
	s_waitcnt vmcnt(4)
	v_cmp_ne_u32_e32 vcc, 0, v15
	s_nop 1
	v_cndmask_b32_e64 v15, 0, 1, vcc
	s_waitcnt vmcnt(2)
	v_cmp_ne_u32_e32 vcc, 0, v17
	s_nop 1
	v_cndmask_b32_e64 v17, 0, 1, vcc
	v_cmp_ne_u32_e32 vcc, 0, v4
	v_mov_b32_e32 v4, s4
	s_nop 0
	v_addc_co_u32_e32 v2, vcc, 0, v2, vcc
	v_cmp_ne_u32_e32 vcc, 0, v6
	s_nop 1
	v_addc_co_u32_e32 v2, vcc, v2, v5, vcc
	v_cmp_ne_u32_e32 vcc, 0, v8
	s_nop 1
	v_addc_co_u32_e32 v2, vcc, v2, v7, vcc
	v_cmp_ne_u32_e32 vcc, 0, v10
	s_nop 1
	v_addc_co_u32_e32 v2, vcc, v2, v9, vcc
	v_cmp_ne_u32_e32 vcc, 0, v12
	s_nop 1
	v_addc_co_u32_e32 v2, vcc, v2, v11, vcc
	v_cmp_ne_u32_e32 vcc, 0, v14
	s_nop 1
	v_addc_co_u32_e32 v2, vcc, v2, v13, vcc
	v_cmp_ne_u32_e32 vcc, 0, v16
	s_nop 1
	v_addc_co_u32_e32 v2, vcc, v2, v15, vcc
	s_waitcnt vmcnt(1)
	v_cmp_ne_u32_e32 vcc, 0, v18
	s_nop 1
	v_addc_co_u32_e32 v2, vcc, v2, v17, vcc
	s_waitcnt vmcnt(0)
	v_readlane_b32 s100, v254, 2
	v_readlane_b32 s101, v254, 3
	s_and_b32 vcc_lo, s2, 7
	s_lshl_b32 vcc_lo, vcc_lo, 2
	s_addk_i32 vcc_lo, 0x3f80
	v_mov_b32_e32 v5, vcc_lo
	s_lshl_b32 vcc_lo, 1, s24
	v_mov_b32_e32 v6, vcc_lo
	s_nop 3
	global_atomic_or v5, v6, s[100:101]
	v_readfirstlane_b32 vcc_lo, v1
	v_readfirstlane_b32 vcc_hi, v2
	s_cmp_lg_u32 vcc_lo, 32
	s_cselect_b32 vcc_lo, 1, 0
	s_cmp_lg_u32 vcc_hi, 8
	s_cselect_b32 vcc_hi, 1, 0
	s_or_b32 vcc_lo, vcc_lo, vcc_hi
	s_cmp_lg_u32 s49, 0x100
	s_cselect_b32 vcc_hi, 1, 0
	s_or_b32 vcc_lo, vcc_lo, vcc_hi
	s_cmp_eq_u32 vcc_lo, 0
	s_cbranch_scc1 .Lnobad
	v_mov_b32_e32 v5, 0x3fa0
	v_mov_b32_e32 v6, 1
	s_nop 1
	global_atomic_add v5, v6, s[100:101]
	s_waitcnt vmcnt(0)
.Lnobad:
	ds_write_b128 v4, v[0:3]

.LBB0_128:
	s_or_b64 exec, exec, s[0:1]
	v_readlane_b32 vcc_lo, v254, 0
	v_readlane_b32 vcc_hi, v254, 1
	s_nop 1
	s_and_saveexec_b64 s[100:101], vcc
	s_cbranch_execz .Lfo_done
	v_readlane_b32 s4, v254, 2
	v_readlane_b32 s5, v254, 3
	v_mov_b32_e32 v8, 0x3f80
	s_nop 3
	global_load_dwordx4 v[0:3], v8, s[4:5] sc1
	global_load_dwordx4 v[4:7], v8, s[4:5] offset:16 sc1
	global_load_dword v9, v8, s[4:5] offset:32 sc1
	s_waitcnt vmcnt(0)
	v_or_b32_e32 v8, v0, v1
	v_or3_b32 v8, v8, v2, v3
	v_or3_b32 v8, v8, v4, v5
	v_or3_b32 v8, v8, v6, v7
	v_bcnt_u32_b32 v8, v8, 0
	v_bcnt_u32_b32 v0, v0, 0
	v_bcnt_u32_b32 v0, v1, v0
	v_bcnt_u32_b32 v0, v2, v0
	v_bcnt_u32_b32 v0, v3, v0
	v_bcnt_u32_b32 v0, v4, v0
	v_bcnt_u32_b32 v0, v5, v0
	v_bcnt_u32_b32 v0, v6, v0
	v_bcnt_u32_b32 v0, v7, v0
	v_cmp_eq_u32_e32 vcc, 8, v8
	s_nop 1
	v_cndmask_b32_e64 v1, 0, 1, vcc
	v_cmp_eq_u32_e32 vcc, 8, v0
	s_nop 1
	v_cndmask_b32_e32 v1, 0, v1, vcc
	v_cmp_eq_u32_e32 vcc, 0, v9
	s_nop 1
	v_cndmask_b32_e32 v1, 0, v1, vcc
	v_mov_b32_e32 v0, 0x200e8
	ds_write_b32 v0, v1
	s_waitcnt lgkmcnt(0)
.Lfo_done:
	s_or_b64 exec, exec, s[100:101]
	s_cmpk_lt_i32 s2, 0x100
	s_cselect_b64 s[0:1], -1, 0
	s_add_u32 s4, s84, 0xbb64300
	s_addc_u32 s5, s85, 0
	v_writelane_b32 v254, s4, 5
	v_cndmask_b32_e64 v0, 0, 1, s[0:1]
	v_cmp_ne_u32_e64 s[0:1], 1, v0
	v_writelane_b32 v254, s5, 6
	s_add_u32 s4, s84, 0xbb67500
	s_addc_u32 s5, s85, 0
	v_writelane_b32 v254, s4, 7
	v_mbcnt_lo_u32_b32 v0, -1, 0
	v_mbcnt_hi_u32_b32 v210, -1, v0
	v_writelane_b32 v254, s5, 8
	s_add_u32 s4, s84, 0xbb67600
	s_addc_u32 s5, s85, 0
	v_writelane_b32 v254, s4, 9
	s_cmpk_lt_i32 s2, 0x680
	s_mov_b32 s57, 0
	v_writelane_b32 v254, s5, 10
	s_cselect_b64 s[4:5], -1, 0
	v_writelane_b32 v254, s4, 11
	s_cmpk_lt_i32 s2, 0x200
	v_and_b32_e32 v0, 64, v210
	v_writelane_b32 v254, s5, 12
	s_cselect_b64 s[4:5], -1, 0
	v_writelane_b32 v254, s4, 13
	s_lshl_b32 s30, s49, 6
	v_mov_b32_e32 v175, 0
	v_writelane_b32 v254, s5, 14
	v_writelane_b32 v254, s2, 15
	s_lshl_b32 s2, s2, 6
	v_writelane_b32 v254, s2, 16
	v_writelane_b32 v254, s0, 17
	s_movk_i32 s75, 0xe000
	s_movk_i32 s73, 0x2000
	v_writelane_b32 v254, s1, 18
	s_add_i32 s0, 0, 0x200f0
	v_writelane_b32 v254, s0, 19
	s_add_i32 s0, 0, 0x14000
	v_writelane_b32 v254, s0, 20
	s_add_i32 s0, 0, 0x18000
	v_writelane_b32 v254, s0, 21
	s_add_i32 s0, 0, 0x1c000
	v_writelane_b32 v254, s0, 22
	s_add_i32 s0, 0, 0x11170
	v_writelane_b32 v254, s0, 23
	s_mov_b32 s83, 0x800000
	v_mov_b32_e32 v209, 1
	s_add_i32 s71, 0, 0x10000
	s_mov_b64 s[60:61], 0x80080
	s_movk_i32 s77, 0x1000
	s_mov_b64 s[62:63], 0x100
	s_mov_b64 s[64:65], 0x80100
	s_mov_b64 s[66:67], 0x180
	s_mov_b64 s[68:69], 0x80180
	s_movk_i32 s90, 0x3400
	s_brev_b32 s70, 60
	s_mov_b32 s72, 0x358637bd
	s_movk_i32 s91, 0xfeff
	s_mov_b32 s80, 0x42b504f3
	s_mov_b32 s74, 0x3e0293ee
	s_mov_b32 s81, 0x29b68000
	v_add_u32_e32 v211, 64, v0
	v_xor_b32_e32 v212, 32, v210
	v_xor_b32_e32 v213, 16, v210
	v_xor_b32_e32 v214, 8, v210
	v_xor_b32_e32 v215, 4, v210
	v_xor_b32_e32 v216, 2, v210
	v_xor_b32_e32 v217, 1, v210
	v_mov_b32_e32 v218, 0x6000
	v_mov_b32_e32 v96, 1.0
	v_mov_b32_e32 v219, 0x3f24fd5c
	v_mov_b32_e32 v220, 0x80
	v_mov_b32_e32 v221, 0xf149f2ca
	s_mov_b64 s[78:79], 0x8000
	s_mov_b64 s[42:43], 0x1a000
	s_mov_b32 s98, s57
	v_writelane_b32 v254, s30, 24
	s_barrier
	s_branch .LBB0_132

.LBB0_132:
	v_mov_b32_e32 v0, 0x20000
	v_readlane_b32 s0, v254, 17
	v_add_u32_e32 v8, 0, v0
	ds_read2_b64 v[0:3], v8 offset1:1
	ds_read2_b64 v[4:7], v8 offset0:10 offset1:12
	ds_read_b64 v[8:9], v8 offset:224
	v_readlane_b32 s1, v254, 18
	s_and_b64 vcc, exec, s[0:1]
	s_mul_i32 s0, s98, 0x1800
	v_writelane_b32 v254, s0, 25
	s_waitcnt lgkmcnt(2)
	v_readfirstlane_b32 s8, v1
	v_readfirstlane_b32 s9, v0
	v_readfirstlane_b32 s10, v3
	v_readfirstlane_b32 s11, v2
	s_waitcnt lgkmcnt(1)
	v_readfirstlane_b32 s5, v5
	v_readfirstlane_b32 s4, v4
	v_readfirstlane_b32 s7, v7
	v_readfirstlane_b32 s6, v6
	s_waitcnt lgkmcnt(0)
	v_readfirstlane_b32 s3, v9
	v_readfirstlane_b32 s2, v8
	v_mov_b32_e32 v0, v208
	v_writelane_b32 v254, s1, 26
	s_mul_i32 s20, s98, 9
	s_cbranch_vccnz .LBB0_141
	s_mul_i32 s18, s98, 0x1800
	s_add_i32 s12, s20, 36
	s_add_i32 s13, s20, 0x48
	s_add_i32 s14, s20, 0x6c
	s_lshl_b32 s56, s98, 11
	v_add_u32_e32 v4, s18, v0
	s_cmp_lg_u32 s98, 0
	v_add_u32_e32 v8, 0x800, v4
	v_ashrrev_i32_e32 v1, 3, v0
	s_cselect_b64 s[0:1], -1, 0
	v_ashrrev_i32_e32 v9, 31, v8
	s_lshl_b32 s15, s98, 12
	v_and_b32_e32 v3, -8, v1
	v_lshlrev_b32_e32 v1, 3, v0
	v_lshl_add_u64 v[52:53], v[8:9], 2, s[6:7]
	v_subrev_u32_e32 v8, s15, v4
	v_and_b32_e32 v2, 0x1f8, v1
	v_ashrrev_i32_e32 v1, 31, v0
	v_ashrrev_i32_e32 v9, 31, v8
	s_ashr_i32 s19, s18, 31
	v_lshl_add_u64 v[56:57], v[8:9], 2, s[4:5]
	v_lshl_add_u64 v[8:9], v[0:1], 0, s[18:19]
	v_lshl_add_u64 v[58:59], v[8:9], 2, s[6:7]
	v_add_u32_e32 v8, 0xa00, v4
	v_ashrrev_i32_e32 v9, 31, v8
	v_lshl_add_u64 v[6:7], v[0:1], 2, s[2:3]
	s_mov_b64 s[16:17], 0xb800000
	v_lshl_add_u64 v[60:61], v[8:9], 2, s[6:7]
	v_lshl_add_u64 v[8:9], v[0:1], 0, s[56:57]
	v_lshl_add_u64 v[50:51], v[6:7], 0, s[16:17]
	s_mov_b64 s[16:17], 0xb802000
	v_lshl_add_u64 v[64:65], v[8:9], 2, s[4:5]
	v_add_u32_e32 v8, 0x400, v4
	v_lshl_add_u64 v[54:55], v[6:7], 0, s[16:17]
	s_mov_b32 s16, s18
	v_ashrrev_i32_e32 v9, 31, v8
	v_writelane_b32 v254, s16, 25
	v_lshl_add_u64 v[66:67], v[8:9], 2, s[6:7]
	v_subrev_u32_e32 v8, s15, v8
	v_ashrrev_i32_e32 v5, 31, v4
	v_writelane_b32 v254, s17, 26
	s_mov_b64 s[16:17], 0xb802800
	v_ashrrev_i32_e32 v9, 31, v8
	v_cmp_lt_i32_e32 vcc, v212, v211
	v_lshl_add_u64 v[48:49], v[4:5], 2, s[6:7]
	v_lshl_add_u64 v[62:63], v[6:7], 0, s[16:17]
	s_mov_b64 s[16:17], 0xb801000
	v_add_u32_e32 v10, 0xc00, v4
	v_lshl_add_u64 v[74:75], v[8:9], 2, s[4:5]
	v_add_u32_e32 v8, 0x600, v4
	v_add_u32_e32 v4, 0xe00, v4
	v_cndmask_b32_e32 v1, v210, v212, vcc
	v_cmp_lt_i32_e32 vcc, v213, v211
	v_lshl_add_u64 v[68:69], v[6:7], 0, s[16:17]
	v_ashrrev_i32_e32 v11, 31, v10
	s_mov_b64 s[16:17], 0xb803000
	v_ashrrev_i32_e32 v9, 31, v8
	v_ashrrev_i32_e32 v5, 31, v4
	v_lshlrev_b32_e32 v101, 2, v1
	v_cndmask_b32_e32 v1, v210, v213, vcc
	v_cmp_lt_i32_e32 vcc, v214, v211
	v_lshl_add_u64 v[70:71], v[10:11], 2, s[6:7]
	v_lshl_add_u64 v[72:73], v[6:7], 0, s[16:17]
	v_lshl_add_u64 v[76:77], v[8:9], 2, s[6:7]
	s_mov_b64 s[16:17], 0xb801800
	v_lshl_add_u64 v[80:81], v[4:5], 2, s[6:7]
	s_mov_b64 s[6:7], 0xb803800
	v_lshlrev_b32_e32 v102, 2, v1
	v_cndmask_b32_e32 v1, v210, v214, vcc
	v_cmp_lt_i32_e32 vcc, v215, v211
	v_lshlrev_b32_e32 v174, 1, v2
	v_lshl_add_u64 v[78:79], v[6:7], 0, s[16:17]
	v_lshl_add_u64 v[82:83], v[6:7], 0, s[6:7]
	v_subrev_u32_e32 v4, s15, v8
	v_lshlrev_b32_e32 v103, 2, v1
	v_cndmask_b32_e32 v1, v210, v215, vcc
	v_cmp_lt_i32_e32 vcc, v216, v211
	v_lshl_add_u64 v[6:7], s[2:3], 0, v[174:175]
	s_mov_b64 s[2:3], 0xfb68100
	v_ashrrev_i32_e32 v5, 31, v4
	v_lshlrev_b32_e32 v104, 2, v1
	v_cndmask_b32_e32 v1, v210, v216, vcc
	v_cmp_lt_i32_e32 vcc, v217, v211
	v_lshl_add_u64 v[86:87], v[6:7], 0, s[2:3]
	s_mov_b64 s[2:3], 0xbb68100
	v_lshl_add_u64 v[84:85], v[4:5], 2, s[4:5]
	v_lshl_add_u32 v97, v0, 2, 0
	v_or_b32_e32 v0, 0x400, v2
	v_or_b32_e32 v4, 0x600, v2
	v_lshlrev_b32_e32 v105, 2, v1
	v_cndmask_b32_e32 v1, v210, v217, vcc
	v_lshl_add_u64 v[88:89], v[6:7], 0, s[2:3]
	v_readlane_b32 s2, v254, 16
	v_lshl_add_u32 v100, v2, 2, 0
	v_lshlrev_b32_e32 v106, 2, v1
	v_add_u32_e32 v107, s2, v3
	v_lshlrev_b32_e32 v174, 2, v2
	v_lshlrev_b32_e32 v90, 2, v0
	v_lshlrev_b32_e32 v92, 2, v4
	v_readlane_b32 s4, v254, 15
	v_mov_b32_e32 v124, 0x200e8
	ds_read_b32 v124, v124
	s_waitcnt lgkmcnt(0)
	v_readfirstlane_b32 s2, v124
	s_cmp_eq_u32 s2, 0
	s_cbranch_scc1 .Lpre_noremap
	s_and_b32 s2, s4, 7
	s_lshl_b32 s2, s2, 5
	s_lshr_b32 s4, s4, 3
	s_or_b32 s4, s4, s2
	s_lshl_b32 s2, s4, 6
	v_add_u32_e32 v107, s2, v3
.Lpre_noremap:
	s_branch .LBB0_135
.LBB0_134:
	s_add_i32 s4, s4, s49
	s_cmpk_gt_i32 s4, 0xff
	v_add_u32_e32 v107, s30, v107
	s_cbranch_scc1 .LBB0_141

.LBB0_141:
	s_waitcnt vmcnt(0)
	s_barrier
	s_and_saveexec_b64 s[0:1], s[46:47]
	s_cbranch_execz .LBB0_178
	v_mov_b32_e32 v0, 0x200e8
	ds_read2_b32 v[0:1], v0 offset1:2
	s_waitcnt lgkmcnt(0)
	v_readfirstlane_b32 s2, v0
	s_cmp_eq_u32 s2, 0
	s_cbranch_scc1 .Lslow_B
	v_readlane_b32 s2, v254, 2
	v_readlane_b32 s3, v254, 3
	v_and_b32_e32 v1, 7, v1
	v_lshlrev_b32_e32 v1, 8, v1
	s_add_u32 s2, s2, 0x480
	s_addc_u32 s3, s3, 0
	s_nop 4
	global_atomic_add v0, v1, v209, s[2:3] sc0
	s_waitcnt vmcnt(0)
	v_or_b32_e32 v0, 31, v0
	v_add_u32_e32 v0, 1, v0
	s_mov_b32 s5, 0
	s_nop 0
	v_readfirstlane_b32 s4, v0
.Llb_B_spin:
	global_load_dword v0, v1, s[2:3] sc1
	s_waitcnt vmcnt(0)
	v_readfirstlane_b32 s6, v0
	s_cmp_lt_u32 s6, s4
	s_cbranch_scc0 .Llb_B_done
	s_add_i32 s5, s5, 1
	s_cmp_lt_u32 s5, 0x40000
	s_cbranch_scc0 .Llb_B_done
	s_sleep 1
	s_branch .Llb_B_spin
.Llb_B_done:
	buffer_inv sc1
	s_waitcnt vmcnt(0)
	s_branch .LBB0_178
.Lslow_B:
	v_readlane_b32 s4, v254, 19
	s_mov_b64 s[2:3], exec
	v_mbcnt_lo_u32_b32 v3, s2, 0
	v_mov_b32_e32 v0, s4
	ds_read_b96 v[0:2], v0
	v_mbcnt_hi_u32_b32 v3, s3, v3
	v_cmp_eq_u32_e32 vcc, 0, v3
	s_waitcnt vmcnt(0) expcnt(0) lgkmcnt(0)
	v_readfirstlane_b32 s4, v0
	s_lshl_b32 s18, s4, 6
	s_and_saveexec_b64 s[4:5], vcc
	s_cbranch_execz .LBB0_144
	s_add_i32 s56, s18, 0x500
	s_lshl_b64 s[6:7], s[56:57], 2
	v_readlane_b32 s8, v254, 2
	v_readlane_b32 s9, v254, 3
	s_add_u32 s6, s8, s6
	s_addc_u32 s7, s9, s7
	s_bcnt1_i32_b64 s2, s[2:3]
	v_mov_b32_e32 v0, s2
	global_atomic_add v0, v175, v0, s[6:7] sc0

.LBB0_560:
	s_cmp_eq_u32 s98, 3
	s_cbranch_scc1 .LBB0_131
	s_waitcnt vmcnt(0)
	s_barrier
	s_and_saveexec_b64 s[0:1], s[46:47]
	s_cbranch_execz .LBB0_130
	v_mov_b32_e32 v0, 0x200e8
	ds_read2_b32 v[0:1], v0 offset1:2
	s_waitcnt lgkmcnt(0)
	v_readfirstlane_b32 s2, v0
	s_cmp_eq_u32 s2, 0
	s_cbranch_scc1 .Lslow_A
	v_readlane_b32 s2, v254, 2
	v_readlane_b32 s3, v254, 3
	v_and_b32_e32 v1, 7, v1
	v_lshlrev_b32_e32 v1, 8, v1
	s_add_u32 s2, s2, 0x480
	s_addc_u32 s3, s3, 0
	s_nop 4
	global_atomic_add v0, v1, v209, s[2:3] sc0
	s_waitcnt vmcnt(0)
	v_or_b32_e32 v0, 31, v0
	v_add_u32_e32 v0, 1, v0
	s_mov_b32 s5, 0
	s_nop 0
	v_readfirstlane_b32 s4, v0
